# speedup vs baseline: 1.0048x; 1.0002x over previous
; template <int BN, bool SWAP> ...
;     ...
;   auto gl = [&](bf16x8 (&ra)[4], bf16x8 (&rb)[NJ], int kt) {
;     const bool nx = (kt >= nk);
;     const bfu* pa = nx ? (chain ? Apn + (kt - nk) * 64 : Ap + (nk - 1) * 64) : Ap + kt * 64;
;     const bfu* pb = nx ? (chain ? Bpn + (kt - nk) * 64 : Bp + (nk - 1) * 64) : Bp + kt * 64;
;     const size_t sa = (nx && chain) ? (size_t)ldan : (size_t)lda, sb = (nx && chain) ? (size_t)ldbn : (size_t)ldb;
; #pragma unroll
;     for (int q = 0; q < 4; ++q) ra[q] = gld16(pa + (size_t)(32 * q) * sa);
; #pragma unroll
;     for (int q = 0; q < NJ; ++q) rb[q] = gld16(pb + (size_t)(32 * q) * sb);
;   };
;   auto wt = [&](bf16x8 (&ra)[4], bf16x8 (&rb)[NJ]) {
;     if (NJ == 4) asm volatile("s_waitcnt vmcnt(8)" : "+v"(ra[0]), "+v"(ra[1]), "+v"(ra[2]), "+v"(ra[3]), "+v"(rb[0]), "+v"(rb[1]), "+v"(rb[NJ - 2]), "+v"(rb[NJ - 1]) : : "memory");
;     else asm volatile("s_waitcnt vmcnt(6)" : "+v"(ra[0]), "+v"(ra[1]), "+v"(ra[2]), "+v"(ra[3]), "+v"(rb[0]), "+v"(rb[1]) : : "memory");
;   };
;   auto st = [&](const bf16x8 (&ra)[4], const bf16x8 (&rb)[NJ], int buf) {
; #pragma unroll
;     for (int q = 0; q < 4; ++q) *(bf16x8*)(As + (buf * 128 + lrow + 32 * q) * 72 + lch) = ra[q];
; #pragma unroll
;     for (int q = 0; q < NJ; ++q) *(bf16x8*)(Bs + (buf * BN + brow + ((SWAP && NJ == 4) ? (8 * (q & 1) + 64 * (q >> 1)) : 32 * q)) * 72 + lch) = rb[q];
;   };
;   auto comp = [&](int buf, auto&& mid) {
;     const bfu* as = As + buf * 128 * 72 + (wr * 64 + c15) * 72 + g * 8;
;     const bfu* bs = Bs + buf * BN * 72 + (wc * (BN / 2) + c15) * 72 + g * 8;
;     {
;       bf16x8 a0[4], b0[NJ];
; #pragma unroll
;       for (int i = 0; i < 4; ++i) a0[i] = *(const bf16x8*)(as + i * 16 * 72);
; #pragma unroll
;       for (int j = 0; j < NJ; ++j) b0[j] = *(const bf16x8*)(bs + j * 16 * 72);
;       mid();
;       __builtin_amdgcn_s_setprio(1);
; #pragma unroll
;       for (int i = 0; i < 4; ++i)
; #pragma unroll
;         for (int j = 0; j < NJ; ++j) acc[i][j] = SWAP ? MFMA16(b0[j], a0[i], acc[i][j]) : MFMA16(a0[i], b0[j], acc[i][j]);
;       __builtin_amdgcn_s_setprio(0);
;     }
;     {
;       bf16x8 a1[4], b1[NJ];
; #pragma unroll
;       for (int i = 0; i < 4; ++i) a1[i] = *(const bf16x8*)(as + i * 16 * 72 + 32);
; #pragma unroll
;       for (int j = 0; j < NJ; ++j) b1[j] = *(const bf16x8*)(bs + j * 16 * 72 + 32);
;       __builtin_amdgcn_s_setprio(1);
.LBB0_485:
	s_add_i32 s20, s19, 2
	s_sub_i32 s2, s15, 64
	s_cmp_lt_u32 s19, 14
	s_cselect_b64 s[22:23], -1, 0
	s_and_b64 vcc, s[22:23], exec
	s_cselect_b32 s2, s2, 0x3c0
	s_lshl_b64 s[22:23], s[2:3], 1
	v_lshl_add_u64 v[120:121], v[98:99], 0, s[22:23]
	global_load_dwordx4 v[108:111], v[120:121], off
	v_lshl_add_u64 v[112:113], v[120:121], 0, s[76:77]
	global_load_dwordx4 v[112:115], v[112:113], off
	v_lshl_add_u64 v[116:117], v[120:121], 0, s[8:9]
	global_load_dwordx4 v[116:119], v[116:117], off
	v_lshl_add_u64 v[120:121], v[120:121], 0, s[78:79]
	v_lshl_add_u64 v[136:137], v[100:101], 0, s[22:23]
	global_load_dwordx4 v[120:123], v[120:121], off
	global_load_dwordx4 v[124:127], v[136:137], off
	v_lshl_add_u64 v[128:129], v[136:137], 0, s[76:77]
	global_load_dwordx4 v[128:131], v[128:129], off
	v_lshl_add_u64 v[132:133], v[136:137], 0, s[8:9]
	global_load_dwordx4 v[132:135], v[132:133], off
	v_lshl_add_u64 v[136:137], v[136:137], 0, s[78:79]
	global_load_dwordx4 v[136:139], v[136:137], off
	ds_read_b128 v[140:143], v104
	ds_read_b128 v[144:147], v104 offset:2304
	ds_read_b128 v[148:151], v104 offset:4608
	ds_read_b128 v[164:167], v104 offset:6912
	ds_read_b128 v[168:171], v105 offset:36864
	ds_read_b128 v[184:187], v105 offset:39168
	ds_read_b128 v[198:201], v105 offset:41472
	ds_read_b128 v[202:205], v105 offset:43776
	s_waitcnt vmcnt(8)
	ds_write_b128 v102, v[40:43] offset:18432
	ds_write_b128 v102, v[44:47] offset:23040
	ds_write_b128 v102, v[48:51] offset:27648
	ds_write_b128 v102, v[52:55] offset:32256
	ds_write_b128 v103, v[56:59] offset:55296
	ds_write_b128 v103, v[60:63] offset:56448
	ds_write_b128 v103, v[64:67] offset:64512
	ds_write_b128 v106, v[72:75] offset:28800
	s_setprio 1
	s_waitcnt lgkmcnt(11)
	v_mfma_f32_16x16x32_bf16 v[40:43], v[168:171], v[140:143], v[92:95]
	s_waitcnt lgkmcnt(10)
	v_mfma_f32_16x16x32_bf16 v[44:47], v[184:187], v[140:143], v[88:91]
	s_waitcnt lgkmcnt(9)
	v_mfma_f32_16x16x32_bf16 v[48:51], v[198:201], v[140:143], v[84:87]
	s_waitcnt lgkmcnt(8)
	v_mfma_f32_16x16x32_bf16 v[52:55], v[202:205], v[140:143], v[80:83]
	v_mfma_f32_16x16x32_bf16 v[56:59], v[168:171], v[144:147], v[76:79]
	v_mfma_f32_16x16x32_bf16 v[60:63], v[184:187], v[144:147], v[68:71]
	v_mfma_f32_16x16x32_bf16 v[36:39], v[198:201], v[144:147], v[36:39]
	v_mfma_f32_16x16x32_bf16 v[32:35], v[202:205], v[144:147], v[32:35]
	v_mfma_f32_16x16x32_bf16 v[28:31], v[168:171], v[148:151], v[28:31]
	v_mfma_f32_16x16x32_bf16 v[24:27], v[184:187], v[148:151], v[24:27]
	v_mfma_f32_16x16x32_bf16 v[20:23], v[198:201], v[148:151], v[20:23]
	v_mfma_f32_16x16x32_bf16 v[16:19], v[202:205], v[148:151], v[16:19]
	v_mfma_f32_16x16x32_bf16 v[12:15], v[168:171], v[164:167], v[12:15]
	v_mfma_f32_16x16x32_bf16 v[8:11], v[184:187], v[164:167], v[8:11]
	v_mfma_f32_16x16x32_bf16 v[4:7], v[198:201], v[164:167], v[4:7]
	v_mfma_f32_16x16x32_bf16 v[0:3], v[202:205], v[164:167], v[0:3]
	s_setprio 0
	ds_read_b128 v[64:67], v104 offset:64
	ds_read_b128 v[68:71], v104 offset:2368
	ds_read_b128 v[72:75], v104 offset:4672
	ds_read_b128 v[76:79], v104 offset:6976
	ds_read_b128 v[80:83], v105 offset:36928
	ds_read_b128 v[84:87], v105 offset:39232
	ds_read_b128 v[88:91], v105 offset:41536
	ds_read_b128 v[92:95], v105 offset:43840
	s_setprio 1
	s_waitcnt lgkmcnt(1)
	v_mfma_f32_16x16x32_bf16 v[36:39], v[88:91], v[68:71], v[36:39]
	s_waitcnt lgkmcnt(0)
	v_mfma_f32_16x16x32_bf16 v[32:35], v[92:95], v[68:71], v[32:35]
	v_mfma_f32_16x16x32_bf16 v[28:31], v[80:83], v[72:75], v[28:31]
	v_mfma_f32_16x16x32_bf16 v[24:27], v[84:87], v[72:75], v[24:27]
	v_mfma_f32_16x16x32_bf16 v[20:23], v[88:91], v[72:75], v[20:23]
	v_mfma_f32_16x16x32_bf16 v[16:19], v[92:95], v[72:75], v[16:19]
	v_mfma_f32_16x16x32_bf16 v[12:15], v[80:83], v[76:79], v[12:15]
	v_mfma_f32_16x16x32_bf16 v[8:11], v[84:87], v[76:79], v[8:11]
	v_mfma_f32_16x16x32_bf16 v[4:7], v[88:91], v[76:79], v[4:7]
	v_mfma_f32_16x16x32_bf16 v[0:3], v[92:95], v[76:79], v[0:3]
	v_mfma_f32_16x16x32_bf16 v[140:143], v[80:83], v[64:67], v[40:43]
	v_mfma_f32_16x16x32_bf16 v[144:147], v[84:87], v[64:67], v[44:47]
	v_mfma_f32_16x16x32_bf16 v[148:151], v[88:91], v[64:67], v[48:51]
	v_mfma_f32_16x16x32_bf16 v[164:167], v[92:95], v[64:67], v[52:55]
	v_mfma_f32_16x16x32_bf16 v[168:171], v[80:83], v[68:71], v[56:59]
	v_mfma_f32_16x16x32_bf16 v[184:187], v[84:87], v[68:71], v[60:63]
	s_setprio 0
	s_cmp_lt_u32 s19, 13
	s_cselect_b32 s2, s15, 0x3c0
	s_lshl_b64 s[22:23], s[2:3], 1
	v_lshl_add_u64 v[52:53], v[98:99], 0, s[22:23]
	s_barrier
; template <int BN, bool SWAP> ...
;     ...
;   auto st = [&](const bf16x8 (&ra)[4], const bf16x8 (&rb)[NJ], int buf) {
; #pragma unroll
;     for (int q = 0; q < 4; ++q) *(bf16x8*)(As + (buf * 128 + lrow + 32 * q) * 72 + lch) = ra[q];
; #pragma unroll
;     for (int q = 0; q < NJ; ++q) *(bf16x8*)(Bs + (buf * BN + brow + ((SWAP && NJ == 4) ? (8 * (q & 1) + 64 * (q >> 1)) : 32 * q)) * 72 + lch) = rb[q];
;   };
;   auto comp = [&](int buf, auto&& mid) {
;     const bfu* as = As + buf * 128 * 72 + (wr * 64 + c15) * 72 + g * 8;
;     const bfu* bs = Bs + buf * BN * 72 + (wc * (BN / 2) + c15) * 72 + g * 8;
;     {
;       bf16x8 a0[4], b0[NJ];
; #pragma unroll
;       for (int i = 0; i < 4; ++i) a0[i] = *(const bf16x8*)(as + i * 16 * 72);
; #pragma unroll
;       for (int j = 0; j < NJ; ++j) b0[j] = *(const bf16x8*)(bs + j * 16 * 72);
;       mid();
;       __builtin_amdgcn_s_setprio(1);
; #pragma unroll
;       for (int i = 0; i < 4; ++i)
; #pragma unroll
;         for (int j = 0; j < NJ; ++j) acc[i][j] = SWAP ? MFMA16(b0[j], a0[i], acc[i][j]) : MFMA16(a0[i], b0[j], acc[i][j]);
;       __builtin_amdgcn_s_setprio(0);
;     }
;     {
;       bf16x8 a1[4], b1[NJ];
; #pragma unroll
;       for (int i = 0; i < 4; ++i) a1[i] = *(const bf16x8*)(as + i * 16 * 72 + 32);
; #pragma unroll
;       for (int j = 0; j < NJ; ++j) b1[j] = *(const bf16x8*)(bs + j * 16 * 72 + 32);
;       __builtin_amdgcn_s_setprio(1);
; #pragma unroll
;       for (int i = 0; i < 4; ++i)
; #pragma unroll
;         for (int j = 0; j < NJ; ++j) acc[i][j] = SWAP ? MFMA16(b1[j], a1[i], acc[i][j]) : MFMA16(a1[i], b1[j], acc[i][j]);
;       __builtin_amdgcn_s_setprio(0);
;     }
; template <int G>
; __device__ __forceinline__ void p5(const Params& P, const Ptrs<G>& w, int pass, int layer, bfu* sm, const XcdInfo& xi) {
;     ...
;     const size_t eb = (size_t)(m0 + wr * 64 + c15) * 1024 + n0 + wc * 64 + 16 * g;
; #pragma unroll
;     for (int i = 0; i < 4; ++i) {
;       const size_t e = eb + (size_t)(16 * i) * 1024;
;       unsigned pk[8];
; #pragma unroll
;       for (int j = 0; j < 4; ++j) {
;         const float4 x0 = *(const float4*)(xres + e + 4 * j);
;         float4 v;
;         v.x = ALPHA_DN * x0.x + C[i][j][0]; v.y = ALPHA_DN * x0.y + C[i][j][1]; v.z = ALPHA_DN * x0.z + C[i][j][2]; v.w = ALPHA_DN * x0.w + C[i][j][3];
;         *(float4*)(w.r() + e + 4 * j) = v;
	global_load_dwordx4 v[40:43], v[52:53], off
	v_lshl_add_u64 v[44:45], v[52:53], 0, s[76:77]
	global_load_dwordx4 v[44:47], v[44:45], off
	v_lshl_add_u64 v[48:49], v[52:53], 0, s[8:9]
	global_load_dwordx4 v[48:51], v[48:49], off
	v_lshl_add_u64 v[52:53], v[52:53], 0, s[78:79]
	v_lshl_add_u64 v[68:69], v[100:101], 0, s[22:23]
	global_load_dwordx4 v[52:55], v[52:53], off
	global_load_dwordx4 v[56:59], v[68:69], off
	v_lshl_add_u64 v[60:61], v[68:69], 0, s[76:77]
	global_load_dwordx4 v[60:63], v[60:61], off
	v_lshl_add_u64 v[64:65], v[68:69], 0, s[8:9]
	global_load_dwordx4 v[64:67], v[64:65], off
	v_lshl_add_u64 v[68:69], v[68:69], 0, s[78:79]
	global_load_dwordx4 v[72:75], v[68:69], off
	ds_read_b128 v[68:71], v104 offset:18432
	ds_read_b128 v[76:79], v104 offset:20736
	ds_read_b128 v[80:83], v104 offset:23040
	ds_read_b128 v[84:87], v104 offset:25344
	ds_read_b128 v[88:91], v105 offset:55296
	ds_read_b128 v[92:95], v105 offset:57600
	ds_read_b128 v[198:201], v105 offset:59904
	ds_read_b128 v[202:205], v105 offset:62208
	s_waitcnt vmcnt(8)
	ds_write_b128 v102, v[108:111]
	ds_write_b128 v102, v[112:115] offset:4608
	ds_write_b128 v102, v[116:119] offset:9216
	ds_write_b128 v102, v[120:123] offset:13824
	ds_write_b128 v103, v[124:127] offset:36864
	ds_write_b128 v103, v[128:131] offset:38016
	ds_write_b128 v103, v[132:135] offset:46080
	ds_write_b128 v103, v[136:139] offset:47232
	s_setprio 1
	s_waitcnt lgkmcnt(11)
	v_mfma_f32_16x16x32_bf16 v[108:111], v[88:91], v[68:71], v[140:143]
	s_waitcnt lgkmcnt(10)
	v_mfma_f32_16x16x32_bf16 v[112:115], v[92:95], v[68:71], v[144:147]
	s_waitcnt lgkmcnt(9)
	v_mfma_f32_16x16x32_bf16 v[116:119], v[198:201], v[68:71], v[148:151]
	s_waitcnt lgkmcnt(8)
	v_mfma_f32_16x16x32_bf16 v[68:71], v[202:205], v[68:71], v[164:167]
	v_mfma_f32_16x16x32_bf16 v[36:39], v[198:201], v[76:79], v[36:39]
	v_mfma_f32_16x16x32_bf16 v[32:35], v[202:205], v[76:79], v[32:35]
	v_mfma_f32_16x16x32_bf16 v[28:31], v[88:91], v[80:83], v[28:31]
	v_mfma_f32_16x16x32_bf16 v[24:27], v[92:95], v[80:83], v[24:27]
	v_mfma_f32_16x16x32_bf16 v[20:23], v[198:201], v[80:83], v[20:23]
	v_mfma_f32_16x16x32_bf16 v[16:19], v[202:205], v[80:83], v[16:19]
	v_mfma_f32_16x16x32_bf16 v[12:15], v[88:91], v[84:87], v[12:15]
	v_mfma_f32_16x16x32_bf16 v[8:11], v[92:95], v[84:87], v[8:11]
	v_mfma_f32_16x16x32_bf16 v[4:7], v[198:201], v[84:87], v[4:7]
	v_mfma_f32_16x16x32_bf16 v[0:3], v[202:205], v[84:87], v[0:3]
	v_mfma_f32_16x16x32_bf16 v[120:123], v[88:91], v[76:79], v[168:171]
	v_mfma_f32_16x16x32_bf16 v[124:127], v[92:95], v[76:79], v[184:187]
	s_setprio 0
	ds_read_b128 v[76:79], v104 offset:18496
	ds_read_b128 v[128:131], v104 offset:20800
	ds_read_b128 v[132:135], v104 offset:23104
	ds_read_b128 v[136:139], v104 offset:25408
	ds_read_b128 v[140:143], v105 offset:55360
	ds_read_b128 v[144:147], v105 offset:57664
	ds_read_b128 v[148:151], v105 offset:59968
	ds_read_b128 v[164:167], v105 offset:62272
	s_setprio 1
	s_waitcnt lgkmcnt(3)
	v_mfma_f32_16x16x32_bf16 v[92:95], v[140:143], v[76:79], v[108:111]
	s_waitcnt lgkmcnt(2)
	v_mfma_f32_16x16x32_bf16 v[88:91], v[144:147], v[76:79], v[112:115]
	s_waitcnt lgkmcnt(1)
	v_mfma_f32_16x16x32_bf16 v[84:87], v[148:151], v[76:79], v[116:119]
	s_waitcnt lgkmcnt(0)
	v_mfma_f32_16x16x32_bf16 v[80:83], v[164:167], v[76:79], v[68:71]
	v_mfma_f32_16x16x32_bf16 v[76:79], v[140:143], v[128:131], v[120:123]
	v_mfma_f32_16x16x32_bf16 v[68:71], v[144:147], v[128:131], v[124:127]
	v_mfma_f32_16x16x32_bf16 v[36:39], v[148:151], v[128:131], v[36:39]
	v_mfma_f32_16x16x32_bf16 v[32:35], v[164:167], v[128:131], v[32:35]
	v_mfma_f32_16x16x32_bf16 v[28:31], v[140:143], v[132:135], v[28:31]
	v_mfma_f32_16x16x32_bf16 v[24:27], v[144:147], v[132:135], v[24:27]
	v_mfma_f32_16x16x32_bf16 v[20:23], v[148:151], v[132:135], v[20:23]
	v_mfma_f32_16x16x32_bf16 v[16:19], v[164:167], v[132:135], v[16:19]
	v_mfma_f32_16x16x32_bf16 v[12:15], v[140:143], v[136:139], v[12:15]
	v_mfma_f32_16x16x32_bf16 v[8:11], v[144:147], v[136:139], v[8:11]
	v_mfma_f32_16x16x32_bf16 v[4:7], v[148:151], v[136:139], v[4:7]
	v_mfma_f32_16x16x32_bf16 v[0:3], v[164:167], v[136:139], v[0:3]
	s_setprio 0
	s_addk_i32 s15, 0x80
	s_mov_b32 s19, s20
	s_barrier
	s_cbranch_vccnz .LBB0_485
	s_waitcnt vmcnt(0)
	s_mov_b32 s20, 0x3fb504f3
	v_add_u32_e32 v40, s14, v97
	v_ashrrev_i32_e32 v41, 31, v40
	v_lshlrev_b64 v[40:41], 10, v[40:41]
	v_mov_b32_e32 v43, s13
	v_or_b32_e32 v42, s12, v96
	v_lshl_add_u64 v[40:41], v[40:41], 0, v[42:43]
	v_lshlrev_b64 v[44:45], 2, v[40:41]
	v_lshl_add_u64 v[46:47], s[0:1], 0, v[44:45]
	global_load_dwordx4 v[48:51], v[46:47], off
	global_load_dwordx4 v[52:55], v[46:47], off offset:16
	global_load_dwordx4 v[56:59], v[46:47], off offset:32
	global_load_dwordx4 v[60:63], v[46:47], off offset:48
	v_lshl_add_u64 v[42:43], s[66:67], 0, v[44:45]
	v_readlane_b32 s12, v253, 38
	v_readlane_b32 s14, v253, 40
	v_readlane_b32 s15, v253, 41
	s_mov_b32 s2, 0x14121000
	v_readlane_b32 s13, v253, 39
	v_lshl_add_u64 v[44:45], s[14:15], 0, v[44:45]
	v_add_co_u32_e32 v72, vcc, s2, v44
	v_readlane_b32 s12, v252, 38
	s_nop 0
	v_addc_co_u32_e32 v73, vcc, 0, v45, vcc
	v_readlane_b32 s13, v252, 39
	s_waitcnt vmcnt(3)
	v_pk_fma_f32 v[48:49], v[48:49], s[20:21], v[92:93] op_sel_hi:[1,0,1]
	v_pk_fma_f32 v[50:51], v[50:51], s[20:21], v[94:95] op_sel_hi:[1,0,1]
	global_store_dwordx4 v[42:43], v[48:51], off
	v_lshl_add_u64 v[40:41], v[40:41], 1, s[12:13]
	v_cvt_pk_bf16_f32 v65, v50, v51
	v_cvt_pk_bf16_f32 v64, v48, v49
	s_waitcnt vmcnt(3)
	v_pk_fma_f32 v[52:53], v[52:53], s[20:21], v[88:89] op_sel_hi:[1,0,1]
	v_pk_fma_f32 v[54:55], v[54:55], s[20:21], v[90:91] op_sel_hi:[1,0,1]
	global_store_dwordx4 v[72:73], v[52:55], off offset:2064
	v_cvt_pk_bf16_f32 v67, v54, v55
	v_cvt_pk_bf16_f32 v66, v52, v53
	s_waitcnt vmcnt(3)
;   __device__ __forceinline__ bfu* rb() const { return (bfu*)(b + L::o_rb); }
;   __device__ __forceinline__ float* r() const { return (float*)(b + L::o_r); }
; template <int G>
; __device__ __forceinline__ void p5(const Params& P, const Ptrs<G>& w, int pass, int layer, bfu* sm, const XcdInfo& xi) {
;     ...
;     for (int i = 0; i < 4; ++i) {
;       const size_t e = eb + (size_t)(16 * i) * 1024;
;       unsigned pk[8];
; #pragma unroll
;       for (int j = 0; j < 4; ++j) {
;         const float4 x0 = *(const float4*)(xres + e + 4 * j);
;         float4 v;
;         v.x = ALPHA_DN * x0.x + C[i][j][0]; v.y = ALPHA_DN * x0.y + C[i][j][1]; v.z = ALPHA_DN * x0.z + C[i][j][2]; v.w = ALPHA_DN * x0.w + C[i][j][3];
;         *(float4*)(w.r() + e + 4 * j) = v;
;         pk[2 * j] = pack2(v.x, v.y); pk[2 * j + 1] = pack2(v.z, v.w);
;       }
;       *(uint4*)(w.rb() + e) = make_uint4(pk[0], pk[1], pk[2], pk[3]);
;       *(uint4*)(w.rb() + e + 8) = make_uint4(pk[4], pk[5], pk[6], pk[7]);
;       __builtin_amdgcn_sched_barrier(0);
;     }
;   }
	v_pk_fma_f32 v[56:57], v[56:57], s[20:21], v[84:85] op_sel_hi:[1,0,1]
	v_pk_fma_f32 v[58:59], v[58:59], s[20:21], v[86:87] op_sel_hi:[1,0,1]
	global_store_dwordx4 v[72:73], v[56:59], off offset:2080
	v_cvt_pk_bf16_f32 v49, v58, v59
	v_cvt_pk_bf16_f32 v48, v56, v57
	s_waitcnt vmcnt(3)
	v_pk_fma_f32 v[52:53], v[60:61], s[20:21], v[80:81] op_sel_hi:[1,0,1]
	v_pk_fma_f32 v[54:55], v[62:63], s[20:21], v[82:83] op_sel_hi:[1,0,1]
	v_cvt_pk_bf16_f32 v50, v52, v53
	v_cvt_pk_bf16_f32 v51, v54, v55
	global_store_dwordx4 v[72:73], v[52:55], off offset:2096
	global_store_dwordx4 v[40:41], v[64:67], off
	global_store_dwordx4 v[40:41], v[48:51], off offset:16
	s_mov_b32 s12, 0x10000
	s_nop 0
	v_add_co_u32_e32 v48, vcc, s12, v46
	v_lshl_add_u64 v[60:61], v[46:47], 0, s[76:77]
	s_nop 0
	v_addc_co_u32_e32 v49, vcc, 0, v47, vcc
	global_load_dwordx4 v[48:51], v[48:49], off
	v_add_co_u32_e32 v52, vcc, s12, v42
	s_mov_b32 s2, 0x14131000
	s_nop 0
	v_addc_co_u32_e32 v53, vcc, 0, v43, vcc
	v_add_co_u32_e32 v62, vcc, s2, v44
	s_waitcnt vmcnt(0)
	v_pk_fma_f32 v[48:49], v[48:49], s[20:21], v[76:77] op_sel_hi:[1,0,1]
	v_pk_fma_f32 v[50:51], v[50:51], s[20:21], v[78:79] op_sel_hi:[1,0,1]
	global_store_dwordx4 v[52:53], v[48:51], off
	global_load_dwordx4 v[52:55], v[60:61], off offset:16
	v_addc_co_u32_e32 v63, vcc, 0, v45, vcc
	s_waitcnt vmcnt(0)
	v_pk_fma_f32 v[52:53], v[52:53], s[20:21], v[68:69] op_sel_hi:[1,0,1]
	v_pk_fma_f32 v[54:55], v[54:55], s[20:21], v[70:71] op_sel_hi:[1,0,1]
	global_store_dwordx4 v[62:63], v[52:55], off offset:2064
	global_load_dwordx4 v[56:59], v[60:61], off offset:32
	s_waitcnt vmcnt(0)
	v_pk_fma_f32 v[36:37], v[56:57], s[20:21], v[36:37] op_sel_hi:[1,0,1]
	v_pk_fma_f32 v[38:39], v[58:59], s[20:21], v[38:39] op_sel_hi:[1,0,1]
	global_store_dwordx4 v[62:63], v[36:39], off offset:2080
	global_load_dwordx4 v[56:59], v[60:61], off offset:48
	v_lshl_add_u64 v[60:61], v[40:41], 0, s[6:7]
	s_waitcnt vmcnt(0)
	v_pk_fma_f32 v[32:33], v[56:57], s[20:21], v[32:33] op_sel_hi:[1,0,1]
	v_cvt_pk_bf16_f32 v56, v48, v49
	v_add_co_u32_e32 v48, vcc, s88, v40
	v_pk_fma_f32 v[34:35], v[58:59], s[20:21], v[34:35] op_sel_hi:[1,0,1]
	v_cvt_pk_bf16_f32 v57, v50, v51
	v_cvt_pk_bf16_f32 v59, v54, v55
	v_cvt_pk_bf16_f32 v58, v52, v53
	v_addc_co_u32_e32 v49, vcc, 0, v41, vcc
	global_store_dwordx4 v[62:63], v[32:35], off offset:2096
	global_store_dwordx4 v[48:49], v[56:59], off
	v_cvt_pk_bf16_f32 v49, v38, v39
	v_cvt_pk_bf16_f32 v51, v34, v35
	v_cvt_pk_bf16_f32 v48, v36, v37
	v_cvt_pk_bf16_f32 v50, v32, v33
	global_store_dwordx4 v[60:61], v[48:51], off offset:16
	s_mov_b32 s2, 0x20000
	v_add_co_u32_e32 v32, vcc, s2, v46
	v_lshl_add_u64 v[36:37], v[46:47], 0, s[8:9]
	s_nop 0
	v_addc_co_u32_e32 v33, vcc, 0, v47, vcc
	global_load_dwordx4 v[32:35], v[32:33], off
	s_mov_b32 s7, 0x20000
	s_waitcnt vmcnt(0)
	v_pk_fma_f32 v[28:29], v[32:33], s[20:21], v[28:29] op_sel_hi:[1,0,1]
	v_add_co_u32_e32 v32, vcc, s2, v42
	v_pk_fma_f32 v[30:31], v[34:35], s[20:21], v[30:31] op_sel_hi:[1,0,1]
	s_nop 0
	v_addc_co_u32_e32 v33, vcc, 0, v43, vcc
	global_store_dwordx4 v[32:33], v[28:31], off
	global_load_dwordx4 v[32:35], v[36:37], off offset:16
	s_mov_b32 s2, 0x14141000
	v_add_co_u32_e32 v38, vcc, s2, v44
	v_cvt_pk_bf16_f32 v31, v30, v31
	s_nop 0
	v_addc_co_u32_e32 v39, vcc, 0, v45, vcc
	v_cvt_pk_bf16_f32 v30, v28, v29
	s_waitcnt vmcnt(0)
	v_pk_fma_f32 v[24:25], v[32:33], s[20:21], v[24:25] op_sel_hi:[1,0,1]
	v_pk_fma_f32 v[26:27], v[34:35], s[20:21], v[26:27] op_sel_hi:[1,0,1]
	global_store_dwordx4 v[38:39], v[24:27], off offset:2064
	global_load_dwordx4 v[32:35], v[36:37], off offset:32
	s_waitcnt vmcnt(0)
	v_pk_fma_f32 v[20:21], v[32:33], s[20:21], v[20:21] op_sel_hi:[1,0,1]
	v_pk_fma_f32 v[22:23], v[34:35], s[20:21], v[22:23] op_sel_hi:[1,0,1]
	global_store_dwordx4 v[38:39], v[20:23], off offset:2080
	global_load_dwordx4 v[32:35], v[36:37], off offset:48
	s_waitcnt vmcnt(0)
	v_pk_fma_f32 v[16:17], v[32:33], s[20:21], v[16:17] op_sel_hi:[1,0,1]
	v_cvt_pk_bf16_f32 v32, v24, v25
	v_add_co_u32_e32 v24, vcc, s12, v40
	v_pk_fma_f32 v[18:19], v[34:35], s[20:21], v[18:19] op_sel_hi:[1,0,1]
	v_cvt_pk_bf16_f32 v33, v26, v27
	v_addc_co_u32_e32 v25, vcc, 0, v41, vcc
	global_store_dwordx4 v[38:39], v[16:19], off offset:2096
	v_lshl_add_u64 v[34:35], v[40:41], 0, s[76:77]
	global_store_dwordx4 v[24:25], v[30:33], off
	v_cvt_pk_bf16_f32 v23, v22, v23
	v_cvt_pk_bf16_f32 v25, v18, v19
	v_cvt_pk_bf16_f32 v22, v20, v21
	v_cvt_pk_bf16_f32 v24, v16, v17
	global_store_dwordx4 v[34:35], v[22:25], off offset:16
	v_add_co_u32_e32 v16, vcc, s75, v46
	v_lshl_add_u64 v[20:21], v[46:47], 0, s[78:79]
	s_nop 0
	v_addc_co_u32_e32 v17, vcc, 0, v47, vcc
	global_load_dwordx4 v[16:19], v[16:17], off
	v_add_co_u32_e32 v22, vcc, s75, v42
	s_mov_b32 s2, 0x14151000
	s_nop 0
	v_addc_co_u32_e32 v23, vcc, 0, v43, vcc
	v_add_co_u32_e32 v24, vcc, s2, v44
	s_mov_b64 s[12:13], 0x18000
	s_nop 0
	v_addc_co_u32_e32 v25, vcc, 0, v45, vcc
	s_mov_b32 s2, 0x18000
	v_lshl_add_u64 v[26:27], v[40:41], 0, s[12:13]
	v_add_co_u32_e32 v28, vcc, s2, v40
	s_waitcnt vmcnt(0)
	v_pk_fma_f32 v[12:13], v[16:17], s[20:21], v[12:13] op_sel_hi:[1,0,1]
	v_pk_fma_f32 v[14:15], v[18:19], s[20:21], v[14:15] op_sel_hi:[1,0,1]
	global_store_dwordx4 v[22:23], v[12:15], off
	global_load_dwordx4 v[16:19], v[20:21], off offset:16
	v_addc_co_u32_e32 v29, vcc, 0, v41, vcc
	s_waitcnt vmcnt(0)
	v_pk_fma_f32 v[8:9], v[16:17], s[20:21], v[8:9] op_sel_hi:[1,0,1]
	v_pk_fma_f32 v[10:11], v[18:19], s[20:21], v[10:11] op_sel_hi:[1,0,1]
	global_store_dwordx4 v[24:25], v[8:11], off offset:2064
	global_load_dwordx4 v[16:19], v[20:21], off offset:32
	v_cvt_pk_bf16_f32 v22, v8, v9
	v_cvt_pk_bf16_f32 v23, v10, v11
	s_waitcnt vmcnt(0)
	v_pk_fma_f32 v[4:5], v[16:17], s[20:21], v[4:5] op_sel_hi:[1,0,1]
	v_pk_fma_f32 v[6:7], v[18:19], s[20:21], v[6:7] op_sel_hi:[1,0,1]
	global_store_dwordx4 v[24:25], v[4:7], off offset:2080
	global_load_dwordx4 v[16:19], v[20:21], off offset:48
	v_cvt_pk_bf16_f32 v21, v14, v15
	v_cvt_pk_bf16_f32 v7, v6, v7
	v_cvt_pk_bf16_f32 v6, v4, v5
	v_cvt_pk_bf16_f32 v20, v12, v13
	s_waitcnt vmcnt(0)
	v_pk_fma_f32 v[0:1], v[16:17], s[20:21], v[0:1] op_sel_hi:[1,0,1]
	v_pk_fma_f32 v[2:3], v[18:19], s[20:21], v[2:3] op_sel_hi:[1,0,1]
	v_cvt_pk_bf16_f32 v8, v0, v1
	v_cvt_pk_bf16_f32 v9, v2, v3
	global_store_dwordx4 v[24:25], v[0:3], off offset:2096
	global_store_dwordx4 v[28:29], v[20:23], off
	global_store_dwordx4 v[26:27], v[6:9], off offset:16
	v_readlane_b32 s2, v254, 27
	s_add_i32 s18, s18, s2
	v_readlane_b32 s2, v254, 34
	s_cmp_lt_i32 s18, s2
	s_cbranch_scc1 .LBB0_480
	v_readlane_b32 s6, v254, 49
